# adds: MLA loop K/V/rope-K tiles fetched HBM->LDS directly (global_load_lds_dwordx4, swizzles on the source addresses) at the top of each step instead of register staging + ds_write_b128
# speedup vs baseline: 1.0047x; 1.0019x over previous
.LBB0_145:
	s_xor_b64 s[30:31], s[18:19], -1
	s_and_b64 s[18:19], s[18:19], exec
	s_cselect_b32 s2, s84, s48
	s_cmp_lg_u64 s[30:31], 0
	s_cselect_b32 s100, 0xffffe000, s96
	s_cselect_b32 s101, -1, 0
	s_movk_i32 s8, 0xd0
	s_or_b32 s18, s34, s2
	s_ashr_i32 s19, s8, 31
	s_add_u32 s36, s0, s8
	s_addc_u32 s37, s1, s19
	s_load_dwordx2 s[36:37], s[36:37], 0x0
	s_mul_hi_u32 s19, s18, 0xa00
	s_mul_i32 s33, s35, 0xa00
	s_mul_i32 s8, s18, 0xa00
	s_add_i32 s19, s19, s33
	s_waitcnt lgkmcnt(0)
	s_add_u32 s8, s36, s8
	s_addc_u32 s19, s37, s19
	s_add_u32 s56, s8, s26
	s_movk_i32 s8, 0xd0
	s_addc_u32 s57, s19, s27
	s_ashr_i32 s19, s8, 31
	s_add_u32 s36, s0, s8
	s_addc_u32 s37, s1, s19
	s_load_dwordx2 s[42:43], s[36:37], 0x0
	v_lshl_add_u64 v[0:1], s[56:57], 0, v[170:171]
	v_lshl_add_u64 v[0:1], v[172:173], 1, v[0:1]
	s_mov_b64 s[56:57], 0x1a800000
	v_lshl_add_u64 v[24:25], v[0:1], 0, s[56:57]
	s_waitcnt lgkmcnt(0)
	s_add_u32 s8, s42, s9
	s_addc_u32 s19, s43, s49
	s_add_u32 s8, s8, s22
	s_addc_u32 s19, s19, s23
	s_add_u32 s36, s8, 0x32800000
	s_movk_i32 s8, 0xd0
	s_addc_u32 s37, s19, 0
	s_ashr_i32 s19, s8, 31
	s_add_u32 s74, s0, s8
	s_addc_u32 s75, s1, s19
	s_movk_i32 s8, 0xd0
	s_load_dwordx2 s[74:75], s[74:75], 0x0
	s_ashr_i32 s19, s8, 31
	s_add_u32 s76, s0, s8
	s_addc_u32 s77, s1, s19
	s_mov_b32 s19, 0x1a800000
	v_add_co_u32_e32 v2, vcc, s19, v0
	s_mov_b32 s8, 16
	s_nop 0
	v_addc_co_u32_e32 v3, vcc, 0, v1, vcc
	s_load_dwordx2 s[78:79], s[76:77], 0x0
	global_load_dwordx4 v[16:19], v[2:3], off
	global_load_dwordx4 v[20:23], v[24:25], off offset:32
	global_load_dwordx4 v[28:31], v[24:25], off offset:64
	global_load_dwordx4 v[32:35], v[24:25], off offset:96
	global_load_dwordx4 v[36:39], v[24:25], off offset:128
	global_load_dwordx4 v[4:7], v[24:25], off offset:352
	global_load_dwordx4 v[68:71], v[24:25], off offset:224
	global_load_dwordx4 v[12:15], v[24:25], off offset:256
	global_load_dwordx4 v[0:3], v[24:25], off offset:288
	global_load_dwordx4 v[8:11], v[24:25], off offset:320
	global_load_dwordx4 v[72:75], v[24:25], off offset:160
	global_load_dwordx4 v[76:79], v[24:25], off offset:192
	s_ashr_i32 s33, s8, 31
	s_add_u32 s76, s0, s8
	s_addc_u32 s77, s1, s33
	s_load_dwordx2 s[76:77], s[76:77], 0x0
	v_add_u32_e32 v26, s18, v167
	v_ashrrev_i32_e32 v27, 31, v26
	global_load_dwordx4 v[80:83], v[174:175], off offset:16
	global_load_dwordx4 v[84:87], v[174:175], off
	s_waitcnt lgkmcnt(0)
	s_add_u32 s8, s74, s20
	v_lshl_add_u64 v[24:25], v[26:27], 2, s[76:77]
	global_load_dword v27, v[24:25], off
	s_addc_u32 s33, s75, s21
	s_mov_b32 s19, s35
	s_mov_b32 s57, 2
	s_add_u32 vcc_lo, s8, 0x3e800000
	s_mov_b32 s8, 0
	s_addc_u32 vcc_hi, s33, 0
	s_waitcnt vmcnt(8)
	v_lshlrev_b32_e32 v24, 16, v68
	v_lshlrev_b32_e32 v102, 16, v20
	v_and_b32_e32 v104, 0xffff0000, v20
	v_and_b32_e32 v90, 0xffff0000, v16
	v_lshlrev_b32_e32 v88, 16, v16
	v_lshlrev_b32_e32 v89, 16, v17
	v_and_b32_e32 v91, 0xffff0000, v17
	v_mul_f32_e32 v17, v90, v90
	v_fmac_f32_e32 v17, v88, v88
	v_fmac_f32_e32 v17, v89, v89
	v_lshlrev_b32_e32 v92, 16, v18
	v_fmac_f32_e32 v17, v91, v91
	v_and_b32_e32 v94, 0xffff0000, v18
	v_fmac_f32_e32 v17, v92, v92
	v_lshlrev_b32_e32 v93, 16, v19
	v_fmac_f32_e32 v17, v94, v94
	v_and_b32_e32 v95, 0xffff0000, v19
	v_fmac_f32_e32 v17, v93, v93
	v_fmac_f32_e32 v17, v95, v95
	v_fmac_f32_e32 v17, v102, v102
	v_lshlrev_b32_e32 v103, 16, v21
	v_fmac_f32_e32 v17, v104, v104
	v_and_b32_e32 v105, 0xffff0000, v21
	v_fmac_f32_e32 v17, v103, v103
	v_lshlrev_b32_e32 v106, 16, v22
	v_fmac_f32_e32 v17, v105, v105
	v_and_b32_e32 v108, 0xffff0000, v22
	v_fmac_f32_e32 v17, v106, v106
	v_lshlrev_b32_e32 v107, 16, v23
	v_fmac_f32_e32 v17, v108, v108
	v_and_b32_e32 v109, 0xffff0000, v23
	v_fmac_f32_e32 v17, v107, v107
	v_lshlrev_b32_e32 v66, 16, v28
	v_fmac_f32_e32 v17, v109, v109
	v_and_b32_e32 v64, 0xffff0000, v28
	v_fmac_f32_e32 v17, v66, v66
	v_lshlrev_b32_e32 v67, 16, v29
	v_fmac_f32_e32 v17, v64, v64
	v_and_b32_e32 v65, 0xffff0000, v29
	v_fmac_f32_e32 v17, v67, v67
	v_lshlrev_b32_e32 v62, 16, v30
	v_fmac_f32_e32 v17, v65, v65
	v_and_b32_e32 v60, 0xffff0000, v30
	v_fmac_f32_e32 v17, v62, v62
	v_lshlrev_b32_e32 v63, 16, v31
	v_fmac_f32_e32 v17, v60, v60
	v_and_b32_e32 v61, 0xffff0000, v31
	v_fmac_f32_e32 v17, v63, v63
	v_lshlrev_b32_e32 v58, 16, v32
	v_fmac_f32_e32 v17, v61, v61
	v_and_b32_e32 v56, 0xffff0000, v32
	v_fmac_f32_e32 v17, v58, v58
	v_lshlrev_b32_e32 v59, 16, v33
	v_fmac_f32_e32 v17, v56, v56
	v_and_b32_e32 v57, 0xffff0000, v33
	v_fmac_f32_e32 v17, v59, v59
	v_lshlrev_b32_e32 v54, 16, v34
	v_fmac_f32_e32 v17, v57, v57
	v_and_b32_e32 v52, 0xffff0000, v34
	v_fmac_f32_e32 v17, v54, v54
	v_lshlrev_b32_e32 v55, 16, v35
	v_fmac_f32_e32 v17, v52, v52
	v_and_b32_e32 v53, 0xffff0000, v35
	v_fmac_f32_e32 v17, v55, v55
	v_lshlrev_b32_e32 v50, 16, v36
	v_fmac_f32_e32 v17, v53, v53
	v_and_b32_e32 v48, 0xffff0000, v36
	v_fmac_f32_e32 v17, v50, v50
	v_lshlrev_b32_e32 v51, 16, v37
	v_fmac_f32_e32 v17, v48, v48
	v_and_b32_e32 v49, 0xffff0000, v37
	v_fmac_f32_e32 v17, v51, v51
	v_lshlrev_b32_e32 v46, 16, v38
	v_fmac_f32_e32 v17, v49, v49
	v_and_b32_e32 v44, 0xffff0000, v38
	v_fmac_f32_e32 v17, v46, v46
	v_fmac_f32_e32 v17, v44, v44
	v_lshlrev_b32_e32 v47, 16, v39
	v_fmac_f32_e32 v17, v47, v47
	v_and_b32_e32 v45, 0xffff0000, v39
	v_fmac_f32_e32 v17, v45, v45
	s_waitcnt vmcnt(4)
	v_lshlrev_b32_e32 v42, 16, v72
	v_fmac_f32_e32 v17, v42, v42
	v_and_b32_e32 v40, 0xffff0000, v72
	v_fmac_f32_e32 v17, v40, v40
	v_lshlrev_b32_e32 v43, 16, v73
	v_fmac_f32_e32 v17, v43, v43
	v_and_b32_e32 v41, 0xffff0000, v73
	v_fmac_f32_e32 v17, v41, v41
	v_lshlrev_b32_e32 v38, 16, v74
	v_fmac_f32_e32 v17, v38, v38
	v_and_b32_e32 v36, 0xffff0000, v74
	v_fmac_f32_e32 v17, v36, v36
	v_lshlrev_b32_e32 v39, 16, v75
	v_fmac_f32_e32 v17, v39, v39
	v_and_b32_e32 v37, 0xffff0000, v75
	v_fmac_f32_e32 v17, v37, v37
	s_waitcnt vmcnt(3)
	v_lshlrev_b32_e32 v34, 16, v76
	v_fmac_f32_e32 v17, v34, v34
	v_and_b32_e32 v32, 0xffff0000, v76
	v_fmac_f32_e32 v17, v32, v32
	v_lshlrev_b32_e32 v35, 16, v77
	v_fmac_f32_e32 v17, v35, v35
	v_and_b32_e32 v33, 0xffff0000, v77
	v_fmac_f32_e32 v17, v33, v33
	v_lshlrev_b32_e32 v30, 16, v78
	v_fmac_f32_e32 v17, v30, v30
	v_and_b32_e32 v28, 0xffff0000, v78
	v_fmac_f32_e32 v17, v28, v28
	v_lshlrev_b32_e32 v31, 16, v79
	v_fmac_f32_e32 v17, v31, v31
	v_and_b32_e32 v29, 0xffff0000, v79
	v_fmac_f32_e32 v17, v29, v29
	v_fmac_f32_e32 v17, v24, v24
	v_and_b32_e32 v22, 0xffff0000, v68
	v_fmac_f32_e32 v17, v22, v22
	v_lshlrev_b32_e32 v25, 16, v69
	v_fmac_f32_e32 v17, v25, v25
	v_and_b32_e32 v23, 0xffff0000, v69
	v_fmac_f32_e32 v17, v23, v23
	v_lshlrev_b32_e32 v16, 16, v70
	v_fmac_f32_e32 v17, v16, v16
	v_and_b32_e32 v18, 0xffff0000, v70
	v_and_b32_e32 v21, 0xffff0000, v71
	v_lshlrev_b32_e32 v20, 16, v71
	v_fmac_f32_e32 v17, v18, v18
	v_pk_mul_f32 v[68:69], v[20:21], v[20:21]
	s_waitcnt vmcnt(1)
	v_mov_b32_e32 v70, v84
	v_add_f32_e32 v17, v17, v68
	v_add_f32_e32 v17, v17, v69
	v_mov_b32_e32 v19, v17
	s_nop 1
	v_permlane32_swap_b32_e32 v17, v19
	v_add_f32_e32 v17, v17, v19
	v_fmamk_f32 v17, v17, 0x3c000000, v253
	v_rsq_f32_e32 v17, v17
	v_mov_b32_e32 v71, v86
	v_mov_b32_e32 v74, v80
	v_mov_b32_e32 v75, v82
	v_mul_f32_e32 v26, 0x3d93cd3a, v17
	s_waitcnt vmcnt(0)
	v_pk_mul_f32 v[68:69], v[26:27], v[88:89] op_sel_hi:[0,1]
	v_pk_mul_f32 v[72:73], v[26:27], v[92:93] op_sel_hi:[0,1]
	v_pk_mul_f32 v[68:69], v[70:71], v[68:69]
	v_pk_mul_f32 v[70:71], v[26:27], v[90:91] op_sel_hi:[0,1]
	v_mov_b32_e32 v86, v85
	v_pk_mul_f32 v[72:73], v[74:75], v[72:73]
	v_pk_mul_f32 v[74:75], v[26:27], v[94:95] op_sel_hi:[0,1]
	v_mov_b32_e32 v82, v81
	v_pk_mul_f32 v[70:71], v[86:87], v[70:71]
	v_pk_mul_f32 v[74:75], v[82:83], v[74:75]
	v_bfe_u32 v76, v71, 16, 1
	v_bfe_u32 v17, v75, 16, 1
	v_bfe_u32 v19, v74, 16, 1
	v_bfe_u32 v77, v70, 16, 1
	v_add3_u32 v70, v70, v77, s64
	v_add3_u32 v71, v71, v76, s64
	v_add3_u32 v19, v74, v19, s64
	v_add3_u32 v17, v75, v17, s64
	v_bfe_u32 v74, v68, 16, 1
	v_bfe_u32 v75, v69, 16, 1
	v_bfe_u32 v76, v72, 16, 1
	v_bfe_u32 v77, v73, 16, 1
	v_add3_u32 v73, v73, v77, s64
	v_add3_u32 v72, v72, v76, s64
	v_add3_u32 v69, v69, v75, s64
	v_add3_u32 v68, v68, v74, s64
	v_lshrrev_b32_e32 v68, 16, v68
	v_lshrrev_b32_e32 v69, 16, v69
	v_lshrrev_b32_e32 v72, 16, v72
	v_lshrrev_b32_e32 v73, 16, v73
	v_and_or_b32 v101, v17, s3, v73
	v_and_or_b32 v100, v19, s3, v72
	v_and_or_b32 v99, v71, s3, v69
	v_and_or_b32 v98, v70, s3, v68
	global_load_dwordx4 v[68:71], v[174:175], off offset:80
	global_load_dwordx4 v[72:75], v[174:175], off offset:64
	v_pk_mul_f32 v[76:77], v[26:27], v[102:103] op_sel_hi:[0,1]
	s_waitcnt vmcnt(0)
	v_mov_b32_e32 v78, v72
	v_mov_b32_e32 v79, v74
	v_pk_mul_f32 v[76:77], v[78:79], v[76:77]
	v_pk_mul_f32 v[78:79], v[26:27], v[104:105] op_sel_hi:[0,1]
	v_mov_b32_e32 v74, v73
	v_pk_mul_f32 v[72:73], v[74:75], v[78:79]
	v_pk_mul_f32 v[74:75], v[26:27], v[106:107] op_sel_hi:[0,1]
	v_mov_b32_e32 v78, v68
	v_mov_b32_e32 v79, v70
	v_pk_mul_f32 v[74:75], v[78:79], v[74:75]
	v_pk_mul_f32 v[78:79], v[26:27], v[108:109] op_sel_hi:[0,1]
	v_mov_b32_e32 v70, v69
	v_pk_mul_f32 v[68:69], v[70:71], v[78:79]
	v_bfe_u32 v70, v73, 16, 1
	v_bfe_u32 v17, v69, 16, 1
	v_bfe_u32 v19, v68, 16, 1
	v_bfe_u32 v71, v72, 16, 1
	v_add3_u32 v71, v72, v71, s64
	v_add3_u32 v70, v73, v70, s64
	v_add3_u32 v19, v68, v19, s64
	v_add3_u32 v17, v69, v17, s64
	v_bfe_u32 v68, v76, 16, 1
	v_bfe_u32 v69, v77, 16, 1
	v_bfe_u32 v72, v74, 16, 1
	v_bfe_u32 v73, v75, 16, 1
	v_add3_u32 v73, v75, v73, s64
	v_add3_u32 v72, v74, v72, s64
	v_add3_u32 v69, v77, v69, s64
	v_add3_u32 v68, v76, v68, s64
	v_lshrrev_b32_e32 v68, 16, v68
	v_lshrrev_b32_e32 v69, 16, v69
	v_lshrrev_b32_e32 v72, 16, v72
	v_lshrrev_b32_e32 v73, 16, v73
	v_and_or_b32 v105, v17, s3, v73
	v_and_or_b32 v104, v19, s3, v72
	v_and_or_b32 v103, v70, s3, v69
	v_and_or_b32 v102, v71, s3, v68
	global_load_dwordx4 v[68:71], v[174:175], off offset:144
	global_load_dwordx4 v[72:75], v[174:175], off offset:128
	v_pk_mul_f32 v[64:65], v[26:27], v[64:65] op_sel_hi:[0,1]
	v_pk_mul_f32 v[60:61], v[26:27], v[60:61] op_sel_hi:[0,1]
	v_pk_mul_f32 v[66:67], v[26:27], v[66:67] op_sel_hi:[0,1]
	v_pk_mul_f32 v[62:63], v[26:27], v[62:63] op_sel_hi:[0,1]
	s_waitcnt vmcnt(0)
	v_mov_b32_e32 v77, v74
	v_mov_b32_e32 v74, v73
	v_mov_b32_e32 v73, v70
	v_mov_b32_e32 v70, v69
	v_mov_b32_e32 v76, v72
	v_pk_mul_f32 v[64:65], v[74:75], v[64:65]
	v_mov_b32_e32 v72, v68
	v_pk_mul_f32 v[60:61], v[70:71], v[60:61]
	v_pk_mul_f32 v[66:67], v[76:77], v[66:67]
	v_pk_mul_f32 v[62:63], v[72:73], v[62:63]
	v_bfe_u32 v17, v61, 16, 1
	v_bfe_u32 v19, v60, 16, 1
	v_bfe_u32 v68, v65, 16, 1
	v_bfe_u32 v69, v64, 16, 1
	v_add3_u32 v64, v64, v69, s64
	v_add3_u32 v65, v65, v68, s64
	v_add3_u32 v19, v60, v19, s64
	v_add3_u32 v17, v61, v17, s64
	v_bfe_u32 v60, v66, 16, 1
	v_bfe_u32 v61, v67, 16, 1
	v_bfe_u32 v68, v62, 16, 1
	v_bfe_u32 v69, v63, 16, 1
	v_add3_u32 v63, v63, v69, s64
	v_add3_u32 v62, v62, v68, s64
	v_add3_u32 v61, v67, v61, s64
	v_add3_u32 v60, v66, v60, s64
	v_lshrrev_b32_e32 v60, 16, v60
	v_lshrrev_b32_e32 v61, 16, v61
	v_lshrrev_b32_e32 v62, 16, v62
	v_lshrrev_b32_e32 v63, 16, v63
	v_and_or_b32 v109, v17, s3, v63
	v_and_or_b32 v108, v19, s3, v62
	v_and_or_b32 v107, v65, s3, v61
	v_and_or_b32 v106, v64, s3, v60
	global_load_dwordx4 v[60:63], v[174:175], off offset:208
	global_load_dwordx4 v[64:67], v[174:175], off offset:192
	v_pk_mul_f32 v[56:57], v[26:27], v[56:57] op_sel_hi:[0,1]
	v_pk_mul_f32 v[52:53], v[26:27], v[52:53] op_sel_hi:[0,1]
	v_pk_mul_f32 v[58:59], v[26:27], v[58:59] op_sel_hi:[0,1]
	v_pk_mul_f32 v[54:55], v[26:27], v[54:55] op_sel_hi:[0,1]
	s_waitcnt vmcnt(0)
	v_mov_b32_e32 v69, v66
	v_mov_b32_e32 v66, v65
	v_mov_b32_e32 v65, v62
	v_mov_b32_e32 v62, v61
	v_mov_b32_e32 v68, v64
	v_pk_mul_f32 v[56:57], v[66:67], v[56:57]
	v_mov_b32_e32 v64, v60
	v_pk_mul_f32 v[52:53], v[62:63], v[52:53]
	v_pk_mul_f32 v[58:59], v[68:69], v[58:59]
	v_pk_mul_f32 v[54:55], v[64:65], v[54:55]
	v_bfe_u32 v17, v53, 16, 1
	v_bfe_u32 v19, v52, 16, 1
	v_bfe_u32 v60, v57, 16, 1
	v_bfe_u32 v61, v56, 16, 1
	v_add3_u32 v56, v56, v61, s64
	v_add3_u32 v57, v57, v60, s64
	v_add3_u32 v19, v52, v19, s64
	v_add3_u32 v17, v53, v17, s64
	v_bfe_u32 v52, v58, 16, 1
	v_bfe_u32 v53, v59, 16, 1
	v_bfe_u32 v60, v54, 16, 1
	v_bfe_u32 v61, v55, 16, 1
	v_add3_u32 v55, v55, v61, s64
	v_add3_u32 v54, v54, v60, s64
	v_add3_u32 v53, v59, v53, s64
	v_add3_u32 v52, v58, v52, s64
	v_lshrrev_b32_e32 v52, 16, v52
	v_lshrrev_b32_e32 v53, 16, v53
	v_lshrrev_b32_e32 v54, 16, v54
	v_lshrrev_b32_e32 v55, 16, v55
	v_and_or_b32 v113, v17, s3, v55
	v_and_or_b32 v112, v19, s3, v54
	v_and_or_b32 v111, v57, s3, v53
	v_and_or_b32 v110, v56, s3, v52
	global_load_dwordx4 v[52:55], v[174:175], off offset:272
	global_load_dwordx4 v[56:59], v[174:175], off offset:256
	v_pk_mul_f32 v[48:49], v[26:27], v[48:49] op_sel_hi:[0,1]
	v_pk_mul_f32 v[44:45], v[26:27], v[44:45] op_sel_hi:[0,1]
	v_pk_mul_f32 v[50:51], v[26:27], v[50:51] op_sel_hi:[0,1]
	v_pk_mul_f32 v[46:47], v[26:27], v[46:47] op_sel_hi:[0,1]
	s_waitcnt vmcnt(0)
	v_mov_b32_e32 v61, v58
	v_mov_b32_e32 v58, v57
	v_mov_b32_e32 v57, v54
	v_mov_b32_e32 v54, v53
	v_mov_b32_e32 v60, v56
	v_pk_mul_f32 v[48:49], v[58:59], v[48:49]
	v_mov_b32_e32 v56, v52
	v_pk_mul_f32 v[44:45], v[54:55], v[44:45]
	v_pk_mul_f32 v[50:51], v[60:61], v[50:51]
	v_pk_mul_f32 v[46:47], v[56:57], v[46:47]
	v_bfe_u32 v17, v45, 16, 1
	v_bfe_u32 v19, v44, 16, 1
	v_bfe_u32 v52, v49, 16, 1
	v_bfe_u32 v53, v48, 16, 1
	v_add3_u32 v48, v48, v53, s64
	v_add3_u32 v49, v49, v52, s64
	v_add3_u32 v19, v44, v19, s64
	v_add3_u32 v17, v45, v17, s64
	v_bfe_u32 v44, v50, 16, 1
	v_bfe_u32 v45, v51, 16, 1
	v_bfe_u32 v52, v46, 16, 1
	v_bfe_u32 v53, v47, 16, 1
	v_add3_u32 v47, v47, v53, s64
	v_add3_u32 v46, v46, v52, s64
	v_add3_u32 v45, v51, v45, s64
	v_add3_u32 v44, v50, v44, s64
	v_lshrrev_b32_e32 v44, 16, v44
	v_lshrrev_b32_e32 v45, 16, v45
	v_lshrrev_b32_e32 v46, 16, v46
	v_lshrrev_b32_e32 v47, 16, v47
	v_and_or_b32 v117, v17, s3, v47
	v_and_or_b32 v116, v19, s3, v46
	v_and_or_b32 v115, v49, s3, v45
	v_and_or_b32 v114, v48, s3, v44
	global_load_dwordx4 v[44:47], v[174:175], off offset:336
	global_load_dwordx4 v[48:51], v[174:175], off offset:320
	v_pk_mul_f32 v[40:41], v[26:27], v[40:41] op_sel_hi:[0,1]
	v_pk_mul_f32 v[36:37], v[26:27], v[36:37] op_sel_hi:[0,1]
	v_pk_mul_f32 v[42:43], v[26:27], v[42:43] op_sel_hi:[0,1]
	v_pk_mul_f32 v[38:39], v[26:27], v[38:39] op_sel_hi:[0,1]
	s_waitcnt vmcnt(0)
	v_mov_b32_e32 v53, v50
	v_mov_b32_e32 v50, v49
	v_mov_b32_e32 v49, v46
	v_mov_b32_e32 v46, v45
	v_mov_b32_e32 v52, v48
	v_pk_mul_f32 v[40:41], v[50:51], v[40:41]
	v_mov_b32_e32 v48, v44
	v_pk_mul_f32 v[36:37], v[46:47], v[36:37]
	v_pk_mul_f32 v[42:43], v[52:53], v[42:43]
	v_pk_mul_f32 v[38:39], v[48:49], v[38:39]
	v_bfe_u32 v17, v37, 16, 1
	v_bfe_u32 v19, v36, 16, 1
	v_bfe_u32 v44, v41, 16, 1
	v_bfe_u32 v45, v40, 16, 1
	v_add3_u32 v40, v40, v45, s64
	v_add3_u32 v41, v41, v44, s64
	v_add3_u32 v19, v36, v19, s64
	v_add3_u32 v17, v37, v17, s64
	v_bfe_u32 v36, v42, 16, 1
	v_bfe_u32 v37, v43, 16, 1
	v_bfe_u32 v44, v38, 16, 1
	v_bfe_u32 v45, v39, 16, 1
	v_add3_u32 v39, v39, v45, s64
	v_add3_u32 v38, v38, v44, s64
	v_add3_u32 v37, v43, v37, s64
	v_add3_u32 v36, v42, v36, s64
	v_lshrrev_b32_e32 v36, 16, v36
	v_lshrrev_b32_e32 v37, 16, v37
	v_lshrrev_b32_e32 v38, 16, v38
	v_lshrrev_b32_e32 v39, 16, v39
	v_and_or_b32 v121, v17, s3, v39
	v_and_or_b32 v120, v19, s3, v38
	v_and_or_b32 v119, v41, s3, v37
	v_and_or_b32 v118, v40, s3, v36
	global_load_dwordx4 v[36:39], v[174:175], off offset:400
	global_load_dwordx4 v[40:43], v[174:175], off offset:384
	v_pk_mul_f32 v[32:33], v[26:27], v[32:33] op_sel_hi:[0,1]
	v_pk_mul_f32 v[28:29], v[26:27], v[28:29] op_sel_hi:[0,1]
	v_pk_mul_f32 v[34:35], v[26:27], v[34:35] op_sel_hi:[0,1]
	v_pk_mul_f32 v[30:31], v[26:27], v[30:31] op_sel_hi:[0,1]
	s_waitcnt vmcnt(0)
	v_mov_b32_e32 v45, v42
	v_mov_b32_e32 v42, v41
	v_mov_b32_e32 v41, v38
	v_mov_b32_e32 v38, v37
	v_mov_b32_e32 v44, v40
	v_pk_mul_f32 v[32:33], v[42:43], v[32:33]
	v_mov_b32_e32 v40, v36
	v_pk_mul_f32 v[28:29], v[38:39], v[28:29]
	v_pk_mul_f32 v[34:35], v[44:45], v[34:35]
	v_pk_mul_f32 v[30:31], v[40:41], v[30:31]
	v_bfe_u32 v17, v29, 16, 1
	v_bfe_u32 v19, v28, 16, 1
	v_bfe_u32 v36, v33, 16, 1
	v_bfe_u32 v37, v32, 16, 1
	v_add3_u32 v32, v32, v37, s64
	v_add3_u32 v33, v33, v36, s64
	v_add3_u32 v19, v28, v19, s64
	v_add3_u32 v17, v29, v17, s64
	v_bfe_u32 v28, v34, 16, 1
	v_bfe_u32 v29, v35, 16, 1
	v_bfe_u32 v36, v30, 16, 1
	v_bfe_u32 v37, v31, 16, 1
	v_add3_u32 v31, v31, v37, s64
	v_add3_u32 v30, v30, v36, s64
	v_add3_u32 v29, v35, v29, s64
	v_add3_u32 v28, v34, v28, s64
	v_lshrrev_b32_e32 v28, 16, v28
	v_lshrrev_b32_e32 v29, 16, v29
	v_lshrrev_b32_e32 v30, 16, v30
	v_lshrrev_b32_e32 v31, 16, v31
	v_and_or_b32 v125, v17, s3, v31
	v_and_or_b32 v124, v19, s3, v30
	v_and_or_b32 v123, v33, s3, v29
	v_and_or_b32 v122, v32, s3, v28
	global_load_dwordx4 v[28:31], v[174:175], off offset:448
	global_load_dwordx4 v[32:35], v[174:175], off offset:464
	v_mov_b32_e32 v17, v20
	v_pk_mul_f32 v[24:25], v[26:27], v[24:25] op_sel_hi:[0,1]
	v_mov_b32_e32 v19, v21
	v_pk_mul_f32 v[16:17], v[26:27], v[16:17] op_sel_hi:[0,1]
	v_pk_mul_f32 v[22:23], v[26:27], v[22:23] op_sel_hi:[0,1]
	v_pk_mul_f32 v[18:19], v[26:27], v[18:19] op_sel_hi:[0,1]
	s_waitcnt vmcnt(1)
	v_mov_b32_e32 v20, v28
	v_mov_b32_e32 v21, v30
	v_mov_b32_e32 v30, v29
	s_waitcnt vmcnt(0)
	v_mov_b32_e32 v28, v32
	v_mov_b32_e32 v29, v34
	v_mov_b32_e32 v34, v33
	v_pk_mul_f32 v[20:21], v[20:21], v[24:25]
	v_pk_mul_f32 v[16:17], v[28:29], v[16:17]
	v_pk_mul_f32 v[22:23], v[30:31], v[22:23]
	v_pk_mul_f32 v[18:19], v[34:35], v[18:19]
	v_bfe_u32 v29, v20, 16, 1
	v_bfe_u32 v30, v21, 16, 1
	v_bfe_u32 v31, v16, 16, 1
	v_bfe_u32 v32, v17, 16, 1
	v_bfe_u32 v24, v19, 16, 1
	v_bfe_u32 v25, v18, 16, 1
	v_bfe_u32 v26, v23, 16, 1
	v_bfe_u32 v28, v22, 16, 1
	v_add3_u32 v17, v17, v32, s64
	v_add3_u32 v16, v16, v31, s64
	v_add3_u32 v21, v21, v30, s64
	v_add3_u32 v20, v20, v29, s64
	v_add3_u32 v22, v22, v28, s64
	v_add3_u32 v23, v23, v26, s64
	v_add3_u32 v18, v18, v25, s64
	v_add3_u32 v19, v19, v24, s64
	v_lshrrev_b32_e32 v20, 16, v20
	v_lshrrev_b32_e32 v21, 16, v21
	v_lshrrev_b32_e32 v16, 16, v16
	v_lshrrev_b32_e32 v17, 16, v17
	v_and_or_b32 v129, v19, s3, v17
	v_and_or_b32 v128, v18, s3, v16
	v_and_or_b32 v127, v23, s3, v21
	v_and_or_b32 v126, v22, s3, v20
	global_load_dwordx4 v[30:33], v[192:193], off
	global_load_dwordx3 v[16:18], v[192:193], off offset:16
	global_load_dword v42, v[190:191], off
	global_load_dword v40, v[190:191], off offset:128
	v_cvt_f32_i32_e32 v146, v27
	v_lshlrev_b32_e32 v24, 16, v6
	v_and_b32_e32 v20, 0xffff0000, v6
	v_and_b32_e32 v23, 0xffff0000, v7
	v_lshlrev_b32_e32 v22, 16, v7
	v_lshlrev_b32_e32 v47, 16, v13
	v_lshlrev_b32_e32 v46, 16, v12
	v_and_b32_e32 v45, 0xffff0000, v13
	v_and_b32_e32 v44, 0xffff0000, v12
	v_lshlrev_b32_e32 v49, 16, v9
	v_lshlrev_b32_e32 v48, 16, v8
	v_and_b32_e32 v51, 0xffff0000, v9
	v_and_b32_e32 v50, 0xffff0000, v8
	v_pk_mul_f32 v[56:57], v[22:23], v[22:23]
	v_pk_mul_f32 v[62:63], v[46:47], v[46:47]
	v_pk_mul_f32 v[64:65], v[44:45], v[44:45]
	v_pk_mul_f32 v[58:59], v[48:49], v[48:49]
	v_pk_mul_f32 v[60:61], v[50:51], v[50:51]
	s_waitcnt vmcnt(3)
	v_mul_f32_e32 v6, v30, v146
	v_cvt_f64_f32_e32 v[6:7], v6
	v_mul_f64 v[12:13], v[6:7], s[82:83]
	v_rndne_f64_e32 v[12:13], v[12:13]
	v_fma_f64 v[6:7], v[6:7], s[82:83], -v[12:13]
	v_cvt_f32_f64_e32 v6, v[6:7]
	v_cos_f32_e32 v12, v6
	v_sin_f32_e32 v26, v6
	global_load_dword v54, v[190:191], off offset:4
	global_load_dword v52, v[190:191], off offset:132
	global_load_dword v43, v[190:191], off offset:8
	global_load_dword v41, v[190:191], off offset:136
	v_mul_f32_e32 v6, v31, v146
	v_cvt_f64_f32_e32 v[6:7], v6
	v_mul_f64 v[8:9], v[6:7], s[82:83]
	v_rndne_f64_e32 v[8:9], v[8:9]
	v_fma_f64 v[6:7], v[6:7], s[82:83], -v[8:9]
	v_cvt_f32_f64_e32 v6, v[6:7]
	v_cos_f32_e32 v28, v6
	v_sin_f32_e32 v30, v6
	global_load_dword v55, v[190:191], off offset:12
	global_load_dword v53, v[190:191], off offset:140
	v_mul_f32_e32 v6, v32, v146
	v_cvt_f64_f32_e32 v[6:7], v6
	v_mul_f64 v[8:9], v[6:7], s[82:83]
	v_rndne_f64_e32 v[8:9], v[8:9]
	v_fma_f64 v[6:7], v[6:7], s[82:83], -v[8:9]
	v_cvt_f32_f64_e32 v6, v[6:7]
	v_cos_f32_e32 v13, v6
	v_sin_f32_e32 v27, v6
	v_mul_f32_e32 v6, v33, v146
	v_cvt_f64_f32_e32 v[6:7], v6
	v_mul_f64 v[8:9], v[6:7], s[82:83]
	v_rndne_f64_e32 v[8:9], v[8:9]
	v_fma_f64 v[6:7], v[6:7], s[82:83], -v[8:9]
	v_cvt_f32_f64_e32 v6, v[6:7]
	v_cos_f32_e32 v29, v6
	v_sin_f32_e32 v31, v6
	global_load_dword v70, v[190:191], off offset:16
	global_load_dword v68, v[190:191], off offset:144
	s_waitcnt vmcnt(10)
	v_mul_f32_e32 v6, v16, v146
	v_cvt_f64_f32_e32 v[6:7], v6
	v_mul_f64 v[8:9], v[6:7], s[82:83]
	v_rndne_f64_e32 v[8:9], v[8:9]
	v_fma_f64 v[6:7], v[6:7], s[82:83], -v[8:9]
	v_cvt_f32_f64_e32 v6, v[6:7]
	v_cos_f32_e32 v16, v6
	v_sin_f32_e32 v32, v6
	v_lshlrev_b32_e32 v67, 16, v15
	v_lshlrev_b32_e32 v66, 16, v14
	v_and_b32_e32 v35, 0xffff0000, v15
	v_and_b32_e32 v34, 0xffff0000, v14
	v_lshlrev_b32_e32 v39, 16, v11
	v_lshlrev_b32_e32 v38, 16, v10
	v_and_b32_e32 v37, 0xffff0000, v11
	v_and_b32_e32 v36, 0xffff0000, v10
	v_pk_mul_f32 v[76:77], v[66:67], v[66:67]
	v_pk_mul_f32 v[78:79], v[34:35], v[34:35]
	v_pk_mul_f32 v[72:73], v[38:39], v[38:39]
	v_pk_mul_f32 v[74:75], v[36:37], v[36:37]
	global_load_dword v82, v[190:191], off offset:20
	global_load_dword v80, v[190:191], off offset:148
	global_load_dword v71, v[190:191], off offset:24
	global_load_dword v69, v[190:191], off offset:152
	v_mul_f32_e32 v6, v17, v146
	v_cvt_f64_f32_e32 v[6:7], v6
	v_mul_f64 v[8:9], v[6:7], s[82:83]
	v_rndne_f64_e32 v[8:9], v[8:9]
	v_fma_f64 v[6:7], v[6:7], s[82:83], -v[8:9]
	v_cvt_f32_f64_e32 v6, v[6:7]
	v_cos_f32_e32 v84, v6
	v_sin_f32_e32 v86, v6
	global_load_dword v10, v[196:197], off
	global_load_dword v83, v[194:195], off
	global_load_dword v81, v[194:195], off offset:128
	v_mul_f32_e32 v6, v18, v146
	v_cvt_f64_f32_e32 v[6:7], v6
	v_mul_f64 v[8:9], v[6:7], s[82:83]
	v_rndne_f64_e32 v[8:9], v[8:9]
	v_fma_f64 v[6:7], v[6:7], s[82:83], -v[8:9]
	v_cvt_f32_f64_e32 v6, v[6:7]
	v_cos_f32_e32 v17, v6
	v_sin_f32_e32 v33, v6
	s_waitcnt vmcnt(2)
	v_mul_f32_e32 v6, v10, v146
	v_cvt_f64_f32_e32 v[6:7], v6
	v_mul_f64 v[8:9], v[6:7], s[82:83]
	v_rndne_f64_e32 v[8:9], v[8:9]
	v_fma_f64 v[6:7], v[6:7], s[82:83], -v[8:9]
	v_cvt_f32_f64_e32 v6, v[6:7]
	v_cos_f32_e32 v85, v6
	v_sin_f32_e32 v87, v6
	global_load_dwordx4 v[6:9], v[192:193], off offset:80
	global_load_dwordx4 v[148:151], v[192:193], off offset:64
	global_load_dword v138, v[190:191], off offset:64
	global_load_dword v94, v[190:191], off offset:192
	v_lshlrev_b32_e32 v89, 16, v1
	v_lshlrev_b32_e32 v88, 16, v0
	v_and_b32_e32 v19, 0xffff0000, v1
	v_and_b32_e32 v18, 0xffff0000, v0
	v_lshlrev_b32_e32 v93, 16, v5
	v_lshlrev_b32_e32 v92, 16, v4
	v_and_b32_e32 v91, 0xffff0000, v5
	v_and_b32_e32 v90, 0xffff0000, v4
	v_pk_mul_f32 v[134:135], v[88:89], v[88:89]
	v_pk_mul_f32 v[136:137], v[18:19], v[18:19]
	v_pk_mul_f32 v[130:131], v[92:93], v[92:93]
	v_pk_mul_f32 v[132:133], v[90:91], v[90:91]
	s_waitcnt vmcnt(2)
	v_mul_f32_e32 v10, v148, v146
	v_cvt_f64_f32_e32 v[10:11], v10
	v_mul_f64 v[14:15], v[10:11], s[82:83]
	v_rndne_f64_e32 v[14:15], v[14:15]
	v_fma_f64 v[10:11], v[10:11], s[82:83], -v[14:15]
	v_cvt_f32_f64_e32 v11, v[10:11]
	v_cos_f32_e32 v10, v11
	v_sin_f32_e32 v14, v11
	global_load_dword v144, v[190:191], off offset:68
	global_load_dword v142, v[190:191], off offset:196
	global_load_dword v139, v[190:191], off offset:72
	global_load_dword v95, v[190:191], off offset:200
	v_mul_f32_e32 v0, v149, v146
	v_cvt_f64_f32_e32 v[0:1], v0
	v_mul_f64 v[4:5], v[0:1], s[82:83]
	v_rndne_f64_e32 v[4:5], v[4:5]
	v_fma_f64 v[0:1], v[0:1], s[82:83], -v[4:5]
	v_cvt_f32_f64_e32 v1, v[0:1]
	v_cos_f32_e32 v0, v1
	v_sin_f32_e32 v4, v1
	global_load_dword v145, v[190:191], off offset:76
	global_load_dword v143, v[190:191], off offset:204
	v_mul_f32_e32 v1, v150, v146
	v_cvt_f64_f32_e32 v[140:141], v1
	v_mul_f64 v[148:149], v[140:141], s[82:83]
	v_rndne_f64_e32 v[148:149], v[148:149]
	v_fma_f64 v[140:141], v[140:141], s[82:83], -v[148:149]
	v_cvt_f32_f64_e32 v1, v[140:141]
	v_cos_f32_e32 v11, v1
	v_sin_f32_e32 v15, v1
	v_mul_f32_e32 v1, v151, v146
	v_cvt_f64_f32_e32 v[140:141], v1
	v_mul_f64 v[148:149], v[140:141], s[82:83]
	v_rndne_f64_e32 v[148:149], v[148:149]
	v_fma_f64 v[140:141], v[140:141], s[82:83], -v[148:149]
	v_cvt_f32_f64_e32 v5, v[140:141]
	v_cos_f32_e32 v1, v5
	v_sin_f32_e32 v5, v5
	v_mul_f32_e32 v6, v6, v146
	v_cvt_f64_f32_e32 v[140:141], v6
	v_add_f32_e32 v6, v62, v64
	v_add_f32_e32 v6, v6, v63
	v_add_f32_e32 v6, v6, v65
	v_add_f32_e32 v6, v6, v76
	v_add_f32_e32 v6, v6, v78
	v_add_f32_e32 v6, v6, v77
	v_add_f32_e32 v6, v6, v79
	v_add_f32_e32 v6, v6, v134
	v_mul_f64 v[148:149], v[140:141], s[82:83]
	v_add_f32_e32 v6, v6, v136
	v_rndne_f64_e32 v[148:149], v[148:149]
	v_lshlrev_b32_e32 v151, 16, v3
	v_lshlrev_b32_e32 v150, 16, v2
	v_add_f32_e32 v6, v6, v135
	v_fma_f64 v[148:149], v[140:141], s[82:83], -v[148:149]
	v_pk_mul_f32 v[152:153], v[150:151], v[150:151]
	v_and_b32_e32 v141, 0xffff0000, v3
	v_and_b32_e32 v140, 0xffff0000, v2
	v_add_f32_e32 v6, v6, v137
	v_pk_mul_f32 v[2:3], v[140:141], v[140:141]
	v_add_f32_e32 v6, v6, v152
	v_add_f32_e32 v2, v6, v2
	v_add_f32_e32 v2, v2, v153
	v_add_f32_e32 v2, v2, v3
	v_add_f32_e32 v2, v2, v58
	v_add_f32_e32 v2, v2, v60
	v_add_f32_e32 v2, v2, v59
	v_add_f32_e32 v2, v2, v61
	v_add_f32_e32 v2, v2, v72
	v_add_f32_e32 v2, v2, v74
	v_add_f32_e32 v2, v2, v73
	v_add_f32_e32 v2, v2, v75
	v_add_f32_e32 v2, v2, v130
	v_add_f32_e32 v2, v2, v132
	v_add_f32_e32 v2, v2, v131
	v_add_f32_e32 v2, v2, v133
	v_fmac_f32_e32 v2, v24, v24
	v_fmac_f32_e32 v2, v20, v20
	v_add_f32_e32 v2, v2, v56
	v_add_f32_e32 v2, v2, v57
	v_mov_b32_e32 v3, v2
	s_nop 1
	v_permlane32_swap_b32_e32 v2, v3
	v_add_f32_e32 v2, v2, v3
	v_fmamk_f32 v2, v2, 0x3c800000, v253
	v_rsq_f32_e32 v3, v2
	v_cvt_f32_f64_e32 v6, v[148:149]
	v_cos_f32_e32 v2, v6
	v_sin_f32_e32 v6, v6
	v_mul_f32_e32 v56, 0x3d93cd3a, v3
	v_pk_mul_f32 v[44:45], v[56:57], v[44:45] op_sel_hi:[0,1]
	v_pk_mul_f32 v[44:45], v[54:55], v[44:45]
	global_load_dword v54, v[190:191], off offset:80
	global_load_dword v58, v[190:191], off offset:208
	v_pk_mul_f32 v[46:47], v[56:57], v[46:47] op_sel_hi:[0,1]
	v_pk_mul_f32 v[42:43], v[42:43], v[46:47]
	v_pk_mul_f32 v[46:47], v[56:57], v[48:49] op_sel_hi:[0,1]
	v_pk_mul_f32 v[40:41], v[40:41], v[46:47]
	v_pk_mul_f32 v[46:47], v[56:57], v[50:51] op_sel_hi:[0,1]
	v_pk_mul_f32 v[46:47], v[52:53], v[46:47]
	v_pk_mul_f32 v[48:49], v[42:43], v[26:27]
	v_pk_mul_f32 v[52:53], v[56:57], v[66:67] op_sel_hi:[0,1]
	v_pk_mul_f32 v[38:39], v[56:57], v[38:39] op_sel_hi:[0,1]
	v_pk_mul_f32 v[26:27], v[40:41], v[26:27]
	v_pk_fma_f32 v[48:49], v[40:41], v[12:13], v[48:49]
	v_pk_mul_f32 v[50:51], v[44:45], v[30:31]
	v_pk_mul_f32 v[52:53], v[70:71], v[52:53]
	v_pk_mul_f32 v[38:39], v[68:69], v[38:39]
	v_pk_mul_f32 v[36:37], v[56:57], v[36:37] op_sel_hi:[0,1]
	v_pk_fma_f32 v[12:13], v[42:43], v[12:13], v[26:27] neg_lo:[0,0,1] neg_hi:[0,0,1]
	v_pk_mul_f32 v[26:27], v[46:47], v[30:31]
	v_pk_fma_f32 v[50:51], v[46:47], v[28:29], v[50:51]
	v_pk_mul_f32 v[34:35], v[56:57], v[34:35] op_sel_hi:[0,1]
	v_pk_mul_f32 v[36:37], v[80:81], v[36:37]
	v_pk_mul_f32 v[60:61], v[52:53], v[32:33]
	v_pk_fma_f32 v[26:27], v[44:45], v[28:29], v[26:27] neg_lo:[0,0,1] neg_hi:[0,0,1]
	v_pk_mul_f32 v[28:29], v[38:39], v[32:33]
	v_pk_mul_f32 v[34:35], v[82:83], v[34:35]
	v_pk_fma_f32 v[60:61], v[38:39], v[16:17], v[60:61]
	v_pk_fma_f32 v[16:17], v[52:53], v[16:17], v[28:29] neg_lo:[0,0,1] neg_hi:[0,0,1]
	v_pk_mul_f32 v[28:29], v[36:37], v[86:87]
	v_bfe_u32 v25, v27, 16, 1
	v_pk_fma_f32 v[28:29], v[34:35], v[84:85], v[28:29] neg_lo:[0,0,1] neg_hi:[0,0,1]
	v_bfe_u32 v30, v26, 16, 1
	v_bfe_u32 v3, v29, 16, 1
	v_bfe_u32 v21, v28, 16, 1
	v_add3_u32 v21, v28, v21, s64
	v_add3_u32 v3, v29, v3, s64
	v_bfe_u32 v28, v13, 16, 1
	v_bfe_u32 v29, v16, 16, 1
	v_add3_u32 v25, v27, v25, s64
	v_bfe_u32 v27, v12, 16, 1
	v_add3_u32 v16, v16, v29, s64
	v_add3_u32 v13, v13, v28, s64
	v_pk_mul_f32 v[62:63], v[34:35], v[86:87]
	v_add3_u32 v26, v26, v30, s64
	v_bfe_u32 v30, v17, 16, 1
	v_add3_u32 v12, v12, v27, s64
	v_lshrrev_b32_e32 v13, 16, v13
	v_lshrrev_b32_e32 v16, 16, v16
	v_pk_fma_f32 v[62:63], v[36:37], v[84:85], v[62:63]
	v_add3_u32 v17, v17, v30, s64
	v_lshrrev_b32_e32 v12, 16, v12
	v_and_or_b32 v132, v21, s3, v16
	v_and_or_b32 v131, v25, s3, v13
	v_bfe_u32 v21, v49, 16, 1
	v_bfe_u32 v25, v60, 16, 1
	v_lshrrev_b32_e32 v17, 16, v17
	v_and_or_b32 v130, v26, s3, v12
	v_bfe_u32 v12, v62, 16, 1
	v_bfe_u32 v13, v51, 16, 1
	v_bfe_u32 v26, v61, 16, 1
	v_add3_u32 v25, v60, v25, s64
	v_add3_u32 v21, v49, v21, s64
	v_and_or_b32 v133, v3, s3, v17
	v_bfe_u32 v3, v63, 16, 1
	v_add3_u32 v13, v51, v13, s64
	v_add3_u32 v12, v62, v12, s64
	v_add3_u32 v26, v61, v26, s64
	v_lshrrev_b32_e32 v21, 16, v21
	v_lshrrev_b32_e32 v25, 16, v25
	v_add3_u32 v3, v63, v3, s64
	v_lshrrev_b32_e32 v26, 16, v26
	v_and_or_b32 v136, v12, s3, v25
	v_and_or_b32 v135, v13, s3, v21
	v_pk_mul_f32 v[12:13], v[56:57], v[88:89] op_sel_hi:[0,1]
	v_bfe_u32 v17, v48, 16, 1
	v_and_or_b32 v137, v3, s3, v26
	s_waitcnt vmcnt(5)
	v_pk_mul_f32 v[26:27], v[138:139], v[12:13]
	v_pk_mul_f32 v[12:13], v[56:57], v[92:93] op_sel_hi:[0,1]
	v_bfe_u32 v16, v50, 16, 1
	v_add3_u32 v17, v48, v17, s64
	s_waitcnt vmcnt(4)
	v_pk_mul_f32 v[28:29], v[94:95], v[12:13]
	v_pk_mul_f32 v[12:13], v[56:57], v[18:19] op_sel_hi:[0,1]
	v_add3_u32 v16, v50, v16, s64
	v_lshrrev_b32_e32 v17, 16, v17
	s_waitcnt vmcnt(3)
	v_pk_mul_f32 v[18:19], v[144:145], v[12:13]
	v_pk_mul_f32 v[12:13], v[56:57], v[90:91] op_sel_hi:[0,1]
	v_and_or_b32 v134, v16, s3, v17
	s_waitcnt vmcnt(2)
	v_pk_mul_f32 v[30:31], v[142:143], v[12:13]
	v_pk_mul_f32 v[12:13], v[26:27], v[14:15]
	v_pk_mul_f32 v[16:17], v[18:19], v[4:5]
	v_pk_fma_f32 v[12:13], v[28:29], v[10:11], v[12:13]
	v_pk_fma_f32 v[16:17], v[30:31], v[0:1], v[16:17]
	global_load_dword v32, v[190:191], off offset:84
	global_load_dword v34, v[190:191], off offset:212
	global_load_dword v55, v[190:191], off offset:88
	global_load_dword v59, v[190:191], off offset:216
	v_mul_f32_e32 v3, v7, v146
	v_cvt_f64_f32_e32 v[38:39], v3
	v_mul_f64 v[40:41], v[38:39], s[82:83]
	v_rndne_f64_e32 v[40:41], v[40:41]
	v_fma_f64 v[38:39], v[38:39], s[82:83], -v[40:41]
	v_cvt_f32_f64_e32 v3, v[38:39]
	v_mov_b32_e32 v25, v22
	v_cos_f32_e32 v22, v3
	v_sin_f32_e32 v38, v3
	v_pk_mul_f32 v[36:37], v[56:57], v[150:151] op_sel_hi:[0,1]
	v_pk_mul_f32 v[24:25], v[56:57], v[24:25] op_sel_hi:[0,1]
	s_waitcnt vmcnt(1)
	v_pk_mul_f32 v[36:37], v[54:55], v[36:37]
	s_waitcnt vmcnt(0)
	v_pk_mul_f32 v[24:25], v[58:59], v[24:25]
	global_load_dword v33, v[190:191], off offset:92
	global_load_dword v35, v[190:191], off offset:220
	v_mov_b32_e32 v21, v23
	v_pk_mul_f32 v[20:21], v[56:57], v[20:21] op_sel_hi:[0,1]
	v_mul_f32_e32 v3, v8, v146
	v_pk_mul_f32 v[40:41], v[56:57], v[140:141] op_sel_hi:[0,1]
	v_mul_f32_e32 v8, v9, v146
	v_cvt_f64_f32_e32 v[8:9], v8
	s_waitcnt vmcnt(1)
	v_pk_mul_f32 v[32:33], v[32:33], v[40:41]
	s_waitcnt vmcnt(0)
	v_pk_mul_f32 v[20:21], v[34:35], v[20:21]
	v_cvt_f64_f32_e32 v[34:35], v3
	v_mul_f64 v[40:41], v[34:35], s[82:83]
	v_rndne_f64_e32 v[40:41], v[40:41]
	v_fma_f64 v[34:35], v[34:35], s[82:83], -v[40:41]
	v_mul_f64 v[40:41], v[8:9], s[82:83]
	v_rndne_f64_e32 v[40:41], v[40:41]
	v_fma_f64 v[8:9], v[8:9], s[82:83], -v[40:41]
	v_cvt_f32_f64_e32 v7, v[34:35]
	v_cvt_f32_f64_e32 v8, v[8:9]
	v_cos_f32_e32 v3, v7
	v_sin_f32_e32 v7, v7
	v_sin_f32_e32 v39, v8
	v_cos_f32_e32 v23, v8
	v_pk_mul_f32 v[34:35], v[36:37], v[6:7]
	v_pk_mul_f32 v[8:9], v[32:33], v[38:39]
	v_pk_fma_f32 v[34:35], v[24:25], v[2:3], v[34:35]
	v_pk_fma_f32 v[8:9], v[20:21], v[22:23], v[8:9]
	v_pk_mul_f32 v[4:5], v[30:31], v[4:5]
	v_pk_mul_f32 v[14:15], v[28:29], v[14:15]
	v_pk_fma_f32 v[0:1], v[18:19], v[0:1], v[4:5] neg_lo:[0,0,1] neg_hi:[0,0,1]
	v_pk_mul_f32 v[4:5], v[24:25], v[6:7]
	v_pk_fma_f32 v[10:11], v[26:27], v[10:11], v[14:15] neg_lo:[0,0,1] neg_hi:[0,0,1]
	v_pk_fma_f32 v[2:3], v[36:37], v[2:3], v[4:5] neg_lo:[0,0,1] neg_hi:[0,0,1]
	v_pk_mul_f32 v[4:5], v[20:21], v[38:39]
	v_bfe_u32 v6, v1, 16, 1
	v_pk_fma_f32 v[4:5], v[32:33], v[22:23], v[4:5] neg_lo:[0,0,1] neg_hi:[0,0,1]
	v_bfe_u32 v7, v0, 16, 1
	v_bfe_u32 v14, v5, 16, 1
	v_bfe_u32 v15, v4, 16, 1
	v_add3_u32 v4, v4, v15, s64
	v_add3_u32 v5, v5, v14, s64
	v_bfe_u32 v14, v10, 16, 1
	v_bfe_u32 v15, v11, 16, 1
	v_add3_u32 v0, v0, v7, s64
	v_add3_u32 v1, v1, v6, s64
	v_bfe_u32 v6, v2, 16, 1
	v_bfe_u32 v7, v3, 16, 1
	v_add3_u32 v11, v11, v15, s64
	v_add3_u32 v10, v10, v14, s64
	v_add3_u32 v3, v3, v7, s64
	v_add3_u32 v2, v2, v6, s64
	v_lshrrev_b32_e32 v6, 16, v10
	v_lshrrev_b32_e32 v7, 16, v11
	v_lshrrev_b32_e32 v2, 16, v2
	v_lshrrev_b32_e32 v3, 16, v3
	v_and_or_b32 v139, v1, s3, v7
	v_and_or_b32 v138, v0, s3, v6
	v_bfe_u32 v6, v12, 16, 1
	v_bfe_u32 v7, v13, 16, 1
	v_and_or_b32 v141, v5, s3, v3
	v_and_or_b32 v140, v4, s3, v2
	v_bfe_u32 v0, v17, 16, 1
	v_bfe_u32 v1, v16, 16, 1
	v_bfe_u32 v4, v34, 16, 1
	v_bfe_u32 v5, v35, 16, 1
	v_add3_u32 v7, v13, v7, s64
	v_add3_u32 v6, v12, v6, s64
	v_bfe_u32 v2, v9, 16, 1
	v_bfe_u32 v3, v8, 16, 1
	v_add3_u32 v1, v16, v1, s64
	v_add3_u32 v0, v17, v0, s64
	v_add3_u32 v5, v35, v5, s64
	v_add3_u32 v4, v34, v4, s64
	v_lshrrev_b32_e32 v6, 16, v6
	v_lshrrev_b32_e32 v7, 16, v7
	v_add3_u32 v3, v8, v3, s64
	v_add3_u32 v2, v9, v2, s64
	v_lshrrev_b32_e32 v4, 16, v4
	v_lshrrev_b32_e32 v5, 16, v5
	v_and_or_b32 v143, v0, s3, v7
	v_and_or_b32 v142, v1, s3, v6
	s_lshr_b32 s55, s2, 6
	s_add_i32 s55, s55, 3
	s_cmp_lg_u64 s[30:31], 0
	s_cselect_b32 s55, s55, 0
	s_mul_i32 s56, s55, 0x30000
	s_add_u32 s36, s36, s56
	s_addc_u32 s37, s37, 0
	s_lshl_b32 s56, s55, 13
	s_add_u32 vcc_lo, vcc_lo, s56
	s_addc_u32 vcc_hi, vcc_hi, 0
	v_and_or_b32 v145, v2, s3, v5
	v_and_or_b32 v144, v3, s3, v4
	v_readlane_b32 s56, v254, 50
	v_bfe_u32 v0, v252, 2, 3
	s_lshl_b32 s55, s56, 3
	v_add_u32_e32 v0, s55, v0
	v_and_b32_e32 v1, 0x33, v0
	v_and_b32_e32 v6, 4, v0
	v_lshl_or_b32 v1, v6, 1, v1
	v_and_b32_e32 v6, 8, v0
	v_lshrrev_b32_e32 v6, 1, v6
	v_or_b32_e32 v1, v1, v6
	v_mul_u32_u24_e32 v1, 0xc00, v1
	v_lshrrev_b32_e32 v6, 5, v252
	v_and_b32_e32 v7, 3, v252
	v_lshlrev_b32_e32 v6, 6, v6
	v_lshl_or_b32 v6, v7, 4, v6
	v_add_u32_e32 v1, v1, v6
	v_add_u32_e32 v14, 0x100, v1
	v_lshrrev_b32_e32 v6, 4, v252
	v_add_u32_e32 v7, s55, v6
	v_and_b32_e32 v8, 15, v252
	v_xor_b32_e32 v9, v8, v6
	v_mul_u32_u24_e32 v10, 0xc00, v7
	v_lshl_add_u32 v16, v9, 4, v10
	v_or_b32_e32 v6, 4, v6
	v_xor_b32_e32 v9, v8, v6
	v_add_u32_e32 v7, 4, v7
	v_mul_u32_u24_e32 v11, 0xc00, v7
	v_lshl_add_u32 v18, v9, 4, v11
	v_lshrrev_b32_e32 v6, 3, v252
	v_add_u32_e32 v6, s55, v6
	v_lshrrev_b32_e32 v7, 1, v6
	v_and_b32_e32 v7, 7, v7
	v_and_b32_e32 v8, 7, v252
	v_xor_b32_e32 v7, v7, v8
	v_lshlrev_b32_e32 v6, 7, v6
	v_lshl_add_u32 v12, v7, 4, v6
	v_mov_b32_e32 v13, 0
	v_mov_b32_e32 v15, 0
	v_mov_b32_e32 v17, 0
	v_mov_b32_e32 v19, 0
	v_lshl_add_u64 v[146:147], v[14:15], 0, s[36:37]
	v_lshl_add_u64 v[148:149], v[16:17], 0, s[36:37]
	v_lshl_add_u64 v[150:151], v[18:19], 0, s[36:37]
	v_lshl_add_u64 v[152:153], v[12:13], 0, vcc
	s_lshl_b32 s55, s56, 11
	s_mov_b32 m0, s55
	s_nop 0
	global_load_lds_dwordx4 v[146:147], off
	s_add_i32 m0, s55, 0x380
	s_nop 0
	global_load_lds_dwordx4 v[146:147], off offset:128
	s_add_i32 m0, s55, 0xc000
	s_nop 0
	global_load_lds_dwordx4 v[148:149], off
	s_add_i32 m0, s55, 0xc400
	s_nop 0
	global_load_lds_dwordx4 v[150:151], off
	s_lshl_b32 s55, s56, 10
	s_add_i32 m0, s55, 0x14000
	s_nop 0
	global_load_lds_dwordx4 v[152:153], off
	s_mul_i32 s42, s100, 24
	s_mov_b32 s43, s101
	v_lshl_add_u64 v[146:147], v[146:147], 0, s[42:43]
	v_lshl_add_u64 v[148:149], v[148:149], 0, s[42:43]
	v_lshl_add_u64 v[150:151], v[150:151], 0, s[42:43]
	v_lshl_add_u64 v[152:153], v[152:153], 0, s[100:101]
	v_readfirstlane_b32 s55, v215
	s_ashr_i32 s56, s55, 6
	s_cmp_gt_i32 s56, 3
	s_cselect_b64 s[80:81], -1, 0
	s_cmp_lt_i32 s56, 4
	s_cselect_b64 s[76:77], -1, 0
	s_and_b32 s55, s55, 0x3fffffc0
	s_lshl_b32 s55, s55, 2
	s_waitcnt vmcnt(0)
	s_lshr_b32 s63, s2, 6
	s_lshl_b32 s56, s56, 5
	s_add_i32 s69, s55, 0
	s_add_i32 s33, s63, 4
	s_add_i32 s2, s56, s2
	s_add_i32 s69, s69, 0x18000
	v_sub_u32_e32 v0, v168, v169
	v_add_u32_e32 v231, s2, v0
	v_lshl_add_u64 v[0:1], s[74:75], 0, v[198:199]
	v_lshl_add_u64 v[0:1], v[0:1], 0, s[20:21]
	s_mov_b64 s[36:37], 0x3e804000
	v_lshl_add_u64 v[206:207], v[0:1], 0, s[36:37]
	v_lshl_add_u64 v[0:1], s[42:43], 0, v[200:201]
	v_lshl_add_u64 v[0:1], v[0:1], 0, s[24:25]
	s_mov_b64 s[36:37], 0x32878100
	v_mov_b32_e32 v32, v97
	v_mov_b32_e32 v33, v97
	v_mov_b32_e32 v46, v97
	v_mov_b32_e32 v47, v97
	v_lshl_add_u64 v[208:209], v[0:1], 0, s[36:37]
	s_add_i32 m0, s33, -5
	s_cmp_lg_u64 s[30:31], 0
	s_cselect_b32 m0, m0, 0
	s_ashr_i32 s37, m0, 19
	s_lshl_b32 s36, m0, 13
	v_lshl_add_u64 v[206:207], v[206:207], 0, s[36:37]
	s_mul_i32 m0, m0, 3
	s_ashr_i32 s37, m0, 16
	s_lshl_b32 s36, m0, 16
	v_lshl_add_u64 v[208:209], v[208:209], 0, s[36:37]
	v_mov_b32_e32 v34, v97
	v_mov_b32_e32 v35, v97
	v_mov_b32_e32 v36, v97
	v_mov_b32_e32 v37, v97
	v_mov_b32_e32 v38, v97
	v_mov_b32_e32 v39, v97
	v_mov_b32_e32 v40, v97
	v_mov_b32_e32 v41, v97
	v_mov_b32_e32 v42, v97
	v_mov_b32_e32 v43, v97
	v_mov_b32_e32 v44, v97
	v_mov_b32_e32 v45, v97
	v_mov_b64_e32 v[62:63], v[46:47]
	v_mov_b64_e32 v[16:17], v[32:33]
	v_mov_b64_e32 v[0:1], v[32:33]
	s_add_i32 s55, s2, 0xfff0001f
	v_lshl_add_u32 v205, v168, 2, s69
	v_lshl_add_u32 v203, v169, 2, s69
	s_sub_i32 s63, -4, s63
	v_mov_b32_e32 v232, 0xf149f2ca
	v_mov_b32_e32 v233, 0
	v_mov_b32_e32 v64, 0
	v_mov_b32_e32 v65, 0
	v_mov_b32_e32 v66, 0
	v_mov_b32_e32 v67, 0
	v_mov_b32_e32 v68, 0
	v_mov_b32_e32 v69, 0
	v_mov_b32_e32 v70, 0
	v_mov_b32_e32 v71, 0
	v_mov_b32_e32 v72, 0
	v_mov_b32_e32 v73, 0
	v_mov_b32_e32 v74, 0
	v_mov_b32_e32 v75, 0
	v_mov_b32_e32 v76, 0
	v_mov_b32_e32 v77, 0
	v_mov_b32_e32 v78, 0
	v_mov_b32_e32 v79, 0
	s_add_i32 s8, s33, -1
	s_cmp_lg_u64 s[30:31], 0
	s_cselect_b32 s8, s8, 0
	s_lshl_b32 s8, s8, 6
	s_sub_i32 s69, 0, s8
	v_mov_b64_e32 v[60:61], v[44:45]
	v_mov_b64_e32 v[58:59], v[42:43]
	v_mov_b64_e32 v[56:57], v[40:41]
	v_mov_b64_e32 v[54:55], v[38:39]
	v_mov_b64_e32 v[52:53], v[36:37]
	v_mov_b64_e32 v[50:51], v[34:35]
	v_mov_b64_e32 v[48:49], v[32:33]
	v_mov_b64_e32 v[18:19], v[34:35]
	v_mov_b64_e32 v[20:21], v[36:37]
	v_mov_b64_e32 v[22:23], v[38:39]
	v_mov_b64_e32 v[24:25], v[40:41]
	v_mov_b64_e32 v[26:27], v[42:43]
	v_mov_b64_e32 v[28:29], v[44:45]
	v_mov_b64_e32 v[30:31], v[46:47]
	v_mov_b64_e32 v[2:3], v[34:35]
	v_mov_b64_e32 v[4:5], v[36:37]
	v_mov_b64_e32 v[6:7], v[38:39]
	v_mov_b64_e32 v[8:9], v[40:41]
	v_mov_b64_e32 v[10:11], v[42:43]
	v_mov_b64_e32 v[12:13], v[44:45]
	v_mov_b64_e32 v[14:15], v[46:47]
	s_mov_b32 s36, 0
	s_mov_b32 s37, 0
	s_waitcnt lgkmcnt(0)
	s_barrier
.LBB0_146:
	s_add_i32 s42, s57, -1
	s_cmp_ge_u32 s42, s33
	s_cbranch_scc1 .Lkvdma_skip
	s_and_b32 s42, s42, 1
	s_add_i32 s43, s36, 1
	s_cmp_lg_u32 s36, 2
	s_cselect_b32 s43, s43, 0
	v_readlane_b32 s74, v254, 50
	s_lshl_b32 s75, s43, 14
	s_lshl_b32 s74, s74, 11
	s_add_i32 s75, s75, s74
	s_mov_b32 m0, s75
	s_nop 0
	global_load_lds_dwordx4 v[146:147], off
	s_add_i32 m0, s75, 0x380
	s_nop 0
	global_load_lds_dwordx4 v[146:147], off offset:128
	s_lshl_b32 s75, s42, 14
	s_add_i32 s75, s75, s74
	s_add_i32 m0, s75, 0xc000
	s_nop 0
	global_load_lds_dwordx4 v[148:149], off
	s_add_i32 m0, s75, 0xc400
	s_nop 0
	global_load_lds_dwordx4 v[150:151], off
	s_lshl_b32 s75, s42, 13
	s_lshr_b32 s74, s74, 1
	s_add_i32 s75, s75, s74
	s_add_i32 m0, s75, 0x14000
	s_nop 0
	global_load_lds_dwordx4 v[152:153], off
	s_mul_i32 s42, s100, 24
	s_mov_b32 s43, s101
	v_lshl_add_u64 v[146:147], v[146:147], 0, s[42:43]
	v_lshl_add_u64 v[148:149], v[148:149], 0, s[42:43]
	v_lshl_add_u64 v[150:151], v[150:151], 0, s[42:43]
	v_lshl_add_u64 v[152:153], v[152:153], 0, s[100:101]

.LBB0_156:
	s_add_i32 s36, s70, 1
	s_cmp_lg_u32 s70, 2
	s_cselect_b32 s36, s36, 0
	s_add_i32 s37, s57, -1
	s_cmp_ge_u32 s37, s33
	s_cbranch_scc1 .LBB0_159
	s_waitcnt vmcnt(0)
